# P3 out-proj epilogue rewritten by hand: residual loads batched 16 at a time (SADDR form), scalar row validity
# speedup vs baseline: 1.0059x; 1.0059x over previous
;     DI void operator()(const f32x4 (&acc)[2][2][4][2], const pg8::Unit& u, int wr, int wc, int fr, int fq) const {
;         const Params& p = *pp;
;         const int colt = u.pn * 256;
; #pragma unroll
;         for (int ai = 0; ai < 2; ++ai)
; #pragma unroll
;             for (int m = 0; m < 4; ++m) {
;                 const int R = u.pm * 256 + ai * 128 + wr * 64 + m * 16 + fr;
;                 const float* xs = nullptr; float* yd = nullptr;
;                 if (R < ROWS_P) { const int b = R / LPAD, t = R - b * LPAD; if (t >= NMETA && t < LP) { const size_t idx = ((size_t)b * SEQ + t - NMETA) * DM; xs = p.x_prompt + idx; yd = p.out + O_YP + idx; } }
;                 else { const size_t idx = (size_t)(R - ROWS_P) * DM; xs = p.x_sample + idx; yd = p.out + O_YS + idx; }
;                 float ss = 0.f;
;                 if (xs) {
; #pragma unroll
;                     for (int bj = 0; bj < 2; ++bj) {
;                         const int n = colt + bj * 128 + wc * 32 + 8 * fq;
;                         const f32x4 x0 = *(const f32x4*)(xs + n), x1 = *(const f32x4*)(xs + n + 4);
;                         const f32x4 h0 = x0 + acc[ai][bj][m][0], h1 = x1 + acc[ai][bj][m][1];
;                         *(f32x4*)(yd + n) = h0; *(f32x4*)(yd + n + 4) = h1;
;                         ss += h0[0] * h0[0] + h0[1] * h0[1] + h0[2] * h0[2] + h0[3] * h0[3] + h1[0] * h1[0] + h1[1] * h1[1] + h1[2] * h1[2] + h1[3] * h1[3];
;                     }
;                 }
;                 ss += __shfl_xor(ss, 16); ss += __shfl_xor(ss, 32);
;                 if (xs && fq == 0) atomicAdd(p.rowss + R, ss);
;             }
;     }
.LBB0_620:
	v_lshl_add_u32 v150, s94, 8, v158
	v_lshl_or_b32 v152, s42, 8, v159
	v_and_b32_e32 v151, 15, v158
	v_lshlrev_b32_e32 v152, 2, v152
	v_lshl_or_b32 v151, v151, 12, v152
	v_lshlrev_b32_e32 v152, 2, v150
	v_xor_b32_e32 v153, 16, v174
	v_xor_b32_e32 v154, 32, v174
	v_lshlrev_b32_e32 v153, 2, v153
	v_lshlrev_b32_e32 v154, 2, v154
	s_and_b64 s[20:21], s[72:73], exec
	s_cselect_b32 s20, 64, 0
	s_lshl_b32 s21, s94, 8
	s_add_i32 s21, s21, s20
	s_cmp_ge_u32 s94, 65
	s_cselect_b32 s96, s78, s76
	s_cselect_b32 s97, s79, s77
	s_cselect_b32 s98, s82, s54
	s_cselect_b32 s99, s83, s55
	s_mov_b32 s19, 0
	s_add_i32 s87, s21, 0
	s_mul_hi_u32 s89, s87, 0x7e07e07f
	s_lshr_b32 s89, s89, 11
	s_mul_i32 s100, s89, 0x1040
	s_sub_i32 s100, s87, s100
	s_add_i32 s100, s100, -16
	s_lshl_b32 s89, s89, 12
	s_add_i32 s89, s89, s100
	s_cmp_lt_u32 s100, 0x1000
	s_cselect_b32 s101, 1, 0
	s_sub_i32 s100, s87, 0x4100
	s_cmp_ge_u32 s94, 65
	s_cselect_b32 s89, s100, s89
	s_cselect_b32 s101, 1, s101
	s_cmp_lg_u32 s101, 0
	s_cselect_b32 s89, s89, 0
	s_lshl_b32 s20, s89, 12
	s_lshl_b32 s101, s101, 0
	s_or_b32 s19, s19, s101
	s_add_u32 s22, s96, s20
	s_addc_u32 s23, s97, 0
	global_load_dwordx4 v[176:179], v151, s[22:23]
	global_load_dwordx4 v[180:183], v151, s[22:23] offset:16
	global_load_dwordx4 v[184:187], v151, s[22:23] offset:512
	global_load_dwordx4 v[188:191], v151, s[22:23] offset:528
	s_add_i32 s87, s21, 16
	s_mul_hi_u32 s89, s87, 0x7e07e07f
	s_lshr_b32 s89, s89, 11
	s_mul_i32 s100, s89, 0x1040
	s_sub_i32 s100, s87, s100
	s_add_i32 s100, s100, -16
	s_lshl_b32 s89, s89, 12
	s_add_i32 s89, s89, s100
	s_cmp_lt_u32 s100, 0x1000
	s_cselect_b32 s101, 1, 0
	s_sub_i32 s100, s87, 0x4100
	s_cmp_ge_u32 s94, 65
	s_cselect_b32 s89, s100, s89
	s_cselect_b32 s101, 1, s101
	s_cmp_lg_u32 s101, 0
	s_cselect_b32 s89, s89, 0
	s_lshl_b32 s42, s89, 12
	s_lshl_b32 s101, s101, 1
	s_or_b32 s19, s19, s101
	s_add_u32 s22, s96, s42
	s_addc_u32 s23, s97, 0
	global_load_dwordx4 v[192:195], v151, s[22:23]
	global_load_dwordx4 v[196:199], v151, s[22:23] offset:16
	global_load_dwordx4 v[200:203], v151, s[22:23] offset:512
	global_load_dwordx4 v[204:207], v151, s[22:23] offset:528
	s_add_i32 s87, s21, 32
	s_mul_hi_u32 s89, s87, 0x7e07e07f
	s_lshr_b32 s89, s89, 11
	s_mul_i32 s100, s89, 0x1040
	s_sub_i32 s100, s87, s100
	s_add_i32 s100, s100, -16
	s_lshl_b32 s89, s89, 12
	s_add_i32 s89, s89, s100
	s_cmp_lt_u32 s100, 0x1000
	s_cselect_b32 s101, 1, 0
	s_sub_i32 s100, s87, 0x4100
	s_cmp_ge_u32 s94, 65
	s_cselect_b32 s89, s100, s89
	s_cselect_b32 s101, 1, s101
	s_cmp_lg_u32 s101, 0
	s_cselect_b32 s89, s89, 0
	s_lshl_b32 s43, s89, 12
	s_lshl_b32 s101, s101, 2
	s_or_b32 s19, s19, s101
	s_add_u32 s22, s96, s43
	s_addc_u32 s23, s97, 0
	global_load_dwordx4 v[208:211], v151, s[22:23]
	global_load_dwordx4 v[212:215], v151, s[22:23] offset:16
	global_load_dwordx4 v[216:219], v151, s[22:23] offset:512
	global_load_dwordx4 v[220:223], v151, s[22:23] offset:528
	s_add_i32 s87, s21, 48
	s_mul_hi_u32 s89, s87, 0x7e07e07f
	s_lshr_b32 s89, s89, 11
	s_mul_i32 s100, s89, 0x1040
	s_sub_i32 s100, s87, s100
	s_add_i32 s100, s100, -16
	s_lshl_b32 s89, s89, 12
	s_add_i32 s89, s89, s100
	s_cmp_lt_u32 s100, 0x1000
	s_cselect_b32 s101, 1, 0
	s_sub_i32 s100, s87, 0x4100
	s_cmp_ge_u32 s94, 65
	s_cselect_b32 s89, s100, s89
	s_cselect_b32 s101, 1, s101
	s_cmp_lg_u32 s101, 0
	s_cselect_b32 s89, s89, 0
	s_lshl_b32 s95, s89, 12
	s_lshl_b32 s101, s101, 3
	s_or_b32 s19, s19, s101
	s_add_u32 s22, s96, s95
	s_addc_u32 s23, s97, 0
	global_load_dwordx4 v[224:227], v151, s[22:23]
	global_load_dwordx4 v[228:231], v151, s[22:23] offset:16
	global_load_dwordx4 v[232:235], v151, s[22:23] offset:512
	global_load_dwordx4 v[236:239], v151, s[22:23] offset:528
	s_waitcnt vmcnt(0)
	v_pk_add_f32 v[124:125], v[124:125], v[176:177]
	v_pk_add_f32 v[126:127], v[126:127], v[178:179]
	v_pk_add_f32 v[120:121], v[120:121], v[180:181]
	v_pk_add_f32 v[122:123], v[122:123], v[182:183]
	v_pk_add_f32 v[116:117], v[116:117], v[184:185]
	v_pk_add_f32 v[118:119], v[118:119], v[186:187]
	v_pk_add_f32 v[112:113], v[112:113], v[188:189]
	v_pk_add_f32 v[114:115], v[114:115], v[190:191]
	v_pk_add_f32 v[108:109], v[108:109], v[192:193]
	v_pk_add_f32 v[110:111], v[110:111], v[194:195]
	v_pk_add_f32 v[104:105], v[104:105], v[196:197]
	v_pk_add_f32 v[106:107], v[106:107], v[198:199]
	v_pk_add_f32 v[100:101], v[100:101], v[200:201]
	v_pk_add_f32 v[102:103], v[102:103], v[202:203]
	v_pk_add_f32 v[96:97], v[96:97], v[204:205]
	v_pk_add_f32 v[98:99], v[98:99], v[206:207]
	v_pk_add_f32 v[92:93], v[92:93], v[208:209]
	v_pk_add_f32 v[94:95], v[94:95], v[210:211]
	v_pk_add_f32 v[88:89], v[88:89], v[212:213]
	v_pk_add_f32 v[90:91], v[90:91], v[214:215]
	v_pk_add_f32 v[84:85], v[84:85], v[216:217]
	v_pk_add_f32 v[86:87], v[86:87], v[218:219]
	v_pk_add_f32 v[80:81], v[80:81], v[220:221]
	v_pk_add_f32 v[82:83], v[82:83], v[222:223]
	v_pk_add_f32 v[76:77], v[76:77], v[224:225]
	v_pk_add_f32 v[78:79], v[78:79], v[226:227]
	v_pk_add_f32 v[72:73], v[72:73], v[228:229]
	v_pk_add_f32 v[74:75], v[74:75], v[230:231]
	v_pk_add_f32 v[68:69], v[68:69], v[232:233]
	v_pk_add_f32 v[70:71], v[70:71], v[234:235]
	v_pk_add_f32 v[64:65], v[64:65], v[236:237]
	v_pk_add_f32 v[66:67], v[66:67], v[238:239]
	v_pk_mul_f32 v[172:173], v[124:125], v[124:125]
	v_pk_fma_f32 v[172:173], v[126:127], v[126:127], v[172:173]
	v_pk_fma_f32 v[172:173], v[120:121], v[120:121], v[172:173]
	v_pk_fma_f32 v[172:173], v[122:123], v[122:123], v[172:173]
	v_pk_fma_f32 v[172:173], v[116:117], v[116:117], v[172:173]
	v_pk_fma_f32 v[172:173], v[118:119], v[118:119], v[172:173]
	v_pk_fma_f32 v[172:173], v[112:113], v[112:113], v[172:173]
	v_pk_fma_f32 v[172:173], v[114:115], v[114:115], v[172:173]
	s_bitcmp1_b32 s19, 0
	s_cbranch_scc0 .Lepi3_skipst_0
	s_add_u32 s22, s98, s20
	s_addc_u32 s23, s99, 0
	global_store_dwordx4 v151, v[124:127], s[22:23]
	global_store_dwordx4 v151, v[120:123], s[22:23] offset:16
	global_store_dwordx4 v151, v[116:119], s[22:23] offset:512
	global_store_dwordx4 v151, v[112:115], s[22:23] offset:528
;     DI void operator()(const f32x4 (&acc)[2][2][4][2], const pg8::Unit& u, int wr, int wc, int fr, int fq) const {
;         const Params& p = *pp;
;         const int colt = u.pn * 256;
; #pragma unroll
;         for (int ai = 0; ai < 2; ++ai)
; #pragma unroll
;             for (int m = 0; m < 4; ++m) {
;                 const int R = u.pm * 256 + ai * 128 + wr * 64 + m * 16 + fr;
;                 const float* xs = nullptr; float* yd = nullptr;
;                 if (R < ROWS_P) { const int b = R / LPAD, t = R - b * LPAD; if (t >= NMETA && t < LP) { const size_t idx = ((size_t)b * SEQ + t - NMETA) * DM; xs = p.x_prompt + idx; yd = p.out + O_YP + idx; } }
;                 else { const size_t idx = (size_t)(R - ROWS_P) * DM; xs = p.x_sample + idx; yd = p.out + O_YS + idx; }
;                 float ss = 0.f;
;                 if (xs) {
; #pragma unroll
;                     for (int bj = 0; bj < 2; ++bj) {
;                         const int n = colt + bj * 128 + wc * 32 + 8 * fq;
;                         const f32x4 x0 = *(const f32x4*)(xs + n), x1 = *(const f32x4*)(xs + n + 4);
;                         const f32x4 h0 = x0 + acc[ai][bj][m][0], h1 = x1 + acc[ai][bj][m][1];
;                         *(f32x4*)(yd + n) = h0; *(f32x4*)(yd + n + 4) = h1;
;                         ss += h0[0] * h0[0] + h0[1] * h0[1] + h0[2] * h0[2] + h0[3] * h0[3] + h1[0] * h1[0] + h1[1] * h1[1] + h1[2] * h1[2] + h1[3] * h1[3];
;                     }
;                 }
;                 ss += __shfl_xor(ss, 16); ss += __shfl_xor(ss, 32);
;                 if (xs && fq == 0) atomicAdd(p.rowss + R, ss);
;             }
;     }
.Lepi3_skipst_0:
	v_add_f32_e32 v168, v172, v173
	s_add_i32 s87, s21, 128
	s_mul_hi_u32 s89, s87, 0x7e07e07f
	s_lshr_b32 s89, s89, 11
	s_mul_i32 s100, s89, 0x1040
	s_sub_i32 s100, s87, s100
	s_add_i32 s100, s100, -16
	s_lshl_b32 s89, s89, 12
	s_add_i32 s89, s89, s100
	s_cmp_lt_u32 s100, 0x1000
	s_cselect_b32 s101, 1, 0
	s_sub_i32 s100, s87, 0x4100
	s_cmp_ge_u32 s94, 65
	s_cselect_b32 s89, s100, s89
	s_cselect_b32 s101, 1, s101
	s_cmp_lg_u32 s101, 0
	s_cselect_b32 s89, s89, 0
	s_lshl_b32 s20, s89, 12
	s_lshl_b32 s101, s101, 4
	s_or_b32 s19, s19, s101
	s_add_u32 s22, s96, s20
	s_addc_u32 s23, s97, 0
	global_load_dwordx4 v[176:179], v151, s[22:23]
	global_load_dwordx4 v[180:183], v151, s[22:23] offset:16
	global_load_dwordx4 v[184:187], v151, s[22:23] offset:512
	global_load_dwordx4 v[188:191], v151, s[22:23] offset:528
	v_pk_mul_f32 v[172:173], v[108:109], v[108:109]
	v_pk_fma_f32 v[172:173], v[110:111], v[110:111], v[172:173]
	v_pk_fma_f32 v[172:173], v[104:105], v[104:105], v[172:173]
	v_pk_fma_f32 v[172:173], v[106:107], v[106:107], v[172:173]
	v_pk_fma_f32 v[172:173], v[100:101], v[100:101], v[172:173]
	v_pk_fma_f32 v[172:173], v[102:103], v[102:103], v[172:173]
	v_pk_fma_f32 v[172:173], v[96:97], v[96:97], v[172:173]
	v_pk_fma_f32 v[172:173], v[98:99], v[98:99], v[172:173]
	s_bitcmp1_b32 s19, 1
	s_cbranch_scc0 .Lepi3_skipst_1
	s_add_u32 s22, s98, s42
	s_addc_u32 s23, s99, 0
	global_store_dwordx4 v151, v[108:111], s[22:23]
	global_store_dwordx4 v151, v[104:107], s[22:23] offset:16
	global_store_dwordx4 v151, v[100:103], s[22:23] offset:512
	global_store_dwordx4 v151, v[96:99], s[22:23] offset:528
.Lepi3_skipst_1:
	v_add_f32_e32 v169, v172, v173
	s_add_i32 s87, s21, 144
	s_mul_hi_u32 s89, s87, 0x7e07e07f
	s_lshr_b32 s89, s89, 11
	s_mul_i32 s100, s89, 0x1040
	s_sub_i32 s100, s87, s100
	s_add_i32 s100, s100, -16
	s_lshl_b32 s89, s89, 12
	s_add_i32 s89, s89, s100
	s_cmp_lt_u32 s100, 0x1000
	s_cselect_b32 s101, 1, 0
	s_sub_i32 s100, s87, 0x4100
	s_cmp_ge_u32 s94, 65
	s_cselect_b32 s89, s100, s89
	s_cselect_b32 s101, 1, s101
	s_cmp_lg_u32 s101, 0
	s_cselect_b32 s89, s89, 0
	s_lshl_b32 s42, s89, 12
	s_lshl_b32 s101, s101, 5
	s_or_b32 s19, s19, s101
	s_add_u32 s22, s96, s42
	s_addc_u32 s23, s97, 0
	global_load_dwordx4 v[192:195], v151, s[22:23]
	global_load_dwordx4 v[196:199], v151, s[22:23] offset:16
	global_load_dwordx4 v[200:203], v151, s[22:23] offset:512
	global_load_dwordx4 v[204:207], v151, s[22:23] offset:528
	v_pk_mul_f32 v[172:173], v[92:93], v[92:93]
	v_pk_fma_f32 v[172:173], v[94:95], v[94:95], v[172:173]
	v_pk_fma_f32 v[172:173], v[88:89], v[88:89], v[172:173]
	v_pk_fma_f32 v[172:173], v[90:91], v[90:91], v[172:173]
	v_pk_fma_f32 v[172:173], v[84:85], v[84:85], v[172:173]
	v_pk_fma_f32 v[172:173], v[86:87], v[86:87], v[172:173]
	v_pk_fma_f32 v[172:173], v[80:81], v[80:81], v[172:173]
	v_pk_fma_f32 v[172:173], v[82:83], v[82:83], v[172:173]
	s_bitcmp1_b32 s19, 2
	s_cbranch_scc0 .Lepi3_skipst_2
	s_add_u32 s22, s98, s43
	s_addc_u32 s23, s99, 0
	global_store_dwordx4 v151, v[92:95], s[22:23]
	global_store_dwordx4 v151, v[88:91], s[22:23] offset:16
	global_store_dwordx4 v151, v[84:87], s[22:23] offset:512
	global_store_dwordx4 v151, v[80:83], s[22:23] offset:528
.Lepi3_skipst_2:
	v_add_f32_e32 v170, v172, v173
	s_add_i32 s87, s21, 160
	s_mul_hi_u32 s89, s87, 0x7e07e07f
	s_lshr_b32 s89, s89, 11
	s_mul_i32 s100, s89, 0x1040
	s_sub_i32 s100, s87, s100
	s_add_i32 s100, s100, -16
	s_lshl_b32 s89, s89, 12
	s_add_i32 s89, s89, s100
	s_cmp_lt_u32 s100, 0x1000
	s_cselect_b32 s101, 1, 0
	s_sub_i32 s100, s87, 0x4100
	s_cmp_ge_u32 s94, 65
	s_cselect_b32 s89, s100, s89
	s_cselect_b32 s101, 1, s101
	s_cmp_lg_u32 s101, 0
	s_cselect_b32 s89, s89, 0
	s_lshl_b32 s43, s89, 12
	s_lshl_b32 s101, s101, 6
	s_or_b32 s19, s19, s101
	s_add_u32 s22, s96, s43
	s_addc_u32 s23, s97, 0
	global_load_dwordx4 v[208:211], v151, s[22:23]
	global_load_dwordx4 v[212:215], v151, s[22:23] offset:16
	global_load_dwordx4 v[216:219], v151, s[22:23] offset:512
	global_load_dwordx4 v[220:223], v151, s[22:23] offset:528
	v_pk_mul_f32 v[172:173], v[76:77], v[76:77]
	v_pk_fma_f32 v[172:173], v[78:79], v[78:79], v[172:173]
	v_pk_fma_f32 v[172:173], v[72:73], v[72:73], v[172:173]
	v_pk_fma_f32 v[172:173], v[74:75], v[74:75], v[172:173]
	v_pk_fma_f32 v[172:173], v[68:69], v[68:69], v[172:173]
	v_pk_fma_f32 v[172:173], v[70:71], v[70:71], v[172:173]
	v_pk_fma_f32 v[172:173], v[64:65], v[64:65], v[172:173]
	v_pk_fma_f32 v[172:173], v[66:67], v[66:67], v[172:173]
	s_bitcmp1_b32 s19, 3
	s_cbranch_scc0 .Lepi3_skipst_3
	s_add_u32 s22, s98, s95
	s_addc_u32 s23, s99, 0
	global_store_dwordx4 v151, v[76:79], s[22:23]
	global_store_dwordx4 v151, v[72:75], s[22:23] offset:16
	global_store_dwordx4 v151, v[68:71], s[22:23] offset:512
	global_store_dwordx4 v151, v[64:67], s[22:23] offset:528
.Lepi3_skipst_3:
	v_add_f32_e32 v171, v172, v173
	s_add_i32 s87, s21, 176
	s_mul_hi_u32 s89, s87, 0x7e07e07f
	s_lshr_b32 s89, s89, 11
	s_mul_i32 s100, s89, 0x1040
	s_sub_i32 s100, s87, s100
	s_add_i32 s100, s100, -16
	s_lshl_b32 s89, s89, 12
	s_add_i32 s89, s89, s100
	s_cmp_lt_u32 s100, 0x1000
	s_cselect_b32 s101, 1, 0
	s_sub_i32 s100, s87, 0x4100
	s_cmp_ge_u32 s94, 65
	s_cselect_b32 s89, s100, s89
	s_cselect_b32 s101, 1, s101
	s_cmp_lg_u32 s101, 0
	s_cselect_b32 s89, s89, 0
	s_lshl_b32 s95, s89, 12
	s_lshl_b32 s101, s101, 7
	s_or_b32 s19, s19, s101
	s_add_u32 s22, s96, s95
	s_addc_u32 s23, s97, 0
	global_load_dwordx4 v[224:227], v151, s[22:23]
	global_load_dwordx4 v[228:231], v151, s[22:23] offset:16
	global_load_dwordx4 v[232:235], v151, s[22:23] offset:512
	global_load_dwordx4 v[236:239], v151, s[22:23] offset:528
	ds_bpermute_b32 v155, v153, v168
	ds_bpermute_b32 v156, v153, v169
	ds_bpermute_b32 v157, v153, v170
	ds_bpermute_b32 v132, v153, v171
	s_waitcnt lgkmcnt(0)
	v_add_f32_e32 v168, v168, v155
	v_add_f32_e32 v169, v169, v156
	v_add_f32_e32 v170, v170, v157
	v_add_f32_e32 v171, v171, v132
	ds_bpermute_b32 v155, v154, v168
	ds_bpermute_b32 v156, v154, v169
	ds_bpermute_b32 v157, v154, v170
	ds_bpermute_b32 v132, v154, v171
	s_waitcnt lgkmcnt(0)
	v_add_f32_e32 v168, v168, v155
	v_add_f32_e32 v169, v169, v156
	v_add_f32_e32 v170, v170, v157
	v_add_f32_e32 v171, v171, v132
	s_mov_b64 exec, s[36:37]
	s_bitcmp1_b32 s19, 0
	s_cbranch_scc0 .Lepi3_skipat_0
	global_atomic_add_f32 v152, v168, s[60:61]
;     DI void operator()(const f32x4 (&acc)[2][2][4][2], const pg8::Unit& u, int wr, int wc, int fr, int fq) const {
;         const Params& p = *pp;
;         const int colt = u.pn * 256;
; #pragma unroll
;         for (int ai = 0; ai < 2; ++ai)
; #pragma unroll
;             for (int m = 0; m < 4; ++m) {
;                 const int R = u.pm * 256 + ai * 128 + wr * 64 + m * 16 + fr;
;                 const float* xs = nullptr; float* yd = nullptr;
;                 if (R < ROWS_P) { const int b = R / LPAD, t = R - b * LPAD; if (t >= NMETA && t < LP) { const size_t idx = ((size_t)b * SEQ + t - NMETA) * DM; xs = p.x_prompt + idx; yd = p.out + O_YP + idx; } }
;                 else { const size_t idx = (size_t)(R - ROWS_P) * DM; xs = p.x_sample + idx; yd = p.out + O_YS + idx; }
;                 float ss = 0.f;
;                 if (xs) {
; #pragma unroll
;                     for (int bj = 0; bj < 2; ++bj) {
;                         const int n = colt + bj * 128 + wc * 32 + 8 * fq;
;                         const f32x4 x0 = *(const f32x4*)(xs + n), x1 = *(const f32x4*)(xs + n + 4);
;                         const f32x4 h0 = x0 + acc[ai][bj][m][0], h1 = x1 + acc[ai][bj][m][1];
;                         *(f32x4*)(yd + n) = h0; *(f32x4*)(yd + n + 4) = h1;
;                         ss += h0[0] * h0[0] + h0[1] * h0[1] + h0[2] * h0[2] + h0[3] * h0[3] + h1[0] * h1[0] + h1[1] * h1[1] + h1[2] * h1[2] + h1[3] * h1[3];
;                     }
;                 }
;                 ss += __shfl_xor(ss, 16); ss += __shfl_xor(ss, 32);
;                 if (xs && fq == 0) atomicAdd(p.rowss + R, ss);
;             }
;     }
.Lepi3_skipat_0:
	s_bitcmp1_b32 s19, 1
	s_cbranch_scc0 .Lepi3_skipat_1
	global_atomic_add_f32 v152, v169, s[60:61] offset:64
.Lepi3_skipat_1:
	s_bitcmp1_b32 s19, 2
	s_cbranch_scc0 .Lepi3_skipat_2
	global_atomic_add_f32 v152, v170, s[60:61] offset:128
.Lepi3_skipat_2:
	s_bitcmp1_b32 s19, 3
	s_cbranch_scc0 .Lepi3_skipat_3
	global_atomic_add_f32 v152, v171, s[60:61] offset:192
.Lepi3_skipat_3:
	s_mov_b64 exec, -1
	s_waitcnt vmcnt(0)
	v_pk_add_f32 v[60:61], v[60:61], v[176:177]
	v_pk_add_f32 v[62:63], v[62:63], v[178:179]
	v_pk_add_f32 v[56:57], v[56:57], v[180:181]
	v_pk_add_f32 v[58:59], v[58:59], v[182:183]
	v_pk_add_f32 v[52:53], v[52:53], v[184:185]
	v_pk_add_f32 v[54:55], v[54:55], v[186:187]
	v_pk_add_f32 v[48:49], v[48:49], v[188:189]
	v_pk_add_f32 v[50:51], v[50:51], v[190:191]
	v_pk_add_f32 v[44:45], v[44:45], v[192:193]
	v_pk_add_f32 v[46:47], v[46:47], v[194:195]
	v_pk_add_f32 v[40:41], v[40:41], v[196:197]
	v_pk_add_f32 v[42:43], v[42:43], v[198:199]
	v_pk_add_f32 v[36:37], v[36:37], v[200:201]
	v_pk_add_f32 v[38:39], v[38:39], v[202:203]
	v_pk_add_f32 v[32:33], v[32:33], v[204:205]
	v_pk_add_f32 v[34:35], v[34:35], v[206:207]
	v_pk_add_f32 v[28:29], v[28:29], v[208:209]
	v_pk_add_f32 v[30:31], v[30:31], v[210:211]
	v_pk_add_f32 v[24:25], v[24:25], v[212:213]
	v_pk_add_f32 v[26:27], v[26:27], v[214:215]
	v_pk_add_f32 v[20:21], v[20:21], v[216:217]
	v_pk_add_f32 v[22:23], v[22:23], v[218:219]
	v_pk_add_f32 v[16:17], v[16:17], v[220:221]
	v_pk_add_f32 v[18:19], v[18:19], v[222:223]
	v_pk_add_f32 v[12:13], v[12:13], v[224:225]
	v_pk_add_f32 v[14:15], v[14:15], v[226:227]
	v_pk_add_f32 v[8:9], v[8:9], v[228:229]
	v_pk_add_f32 v[10:11], v[10:11], v[230:231]
	v_pk_add_f32 v[4:5], v[4:5], v[232:233]
	v_pk_add_f32 v[6:7], v[6:7], v[234:235]
	v_pk_add_f32 v[0:1], v[0:1], v[236:237]
	v_pk_add_f32 v[2:3], v[2:3], v[238:239]
	v_pk_mul_f32 v[172:173], v[60:61], v[60:61]
	v_pk_fma_f32 v[172:173], v[62:63], v[62:63], v[172:173]
	v_pk_fma_f32 v[172:173], v[56:57], v[56:57], v[172:173]
	v_pk_fma_f32 v[172:173], v[58:59], v[58:59], v[172:173]
	v_pk_fma_f32 v[172:173], v[52:53], v[52:53], v[172:173]
	v_pk_fma_f32 v[172:173], v[54:55], v[54:55], v[172:173]
	v_pk_fma_f32 v[172:173], v[48:49], v[48:49], v[172:173]
	v_pk_fma_f32 v[172:173], v[50:51], v[50:51], v[172:173]
	s_bitcmp1_b32 s19, 4
	s_cbranch_scc0 .Lepi3_skipst_4
	s_add_u32 s22, s98, s20
	s_addc_u32 s23, s99, 0
	global_store_dwordx4 v151, v[60:63], s[22:23]
	global_store_dwordx4 v151, v[56:59], s[22:23] offset:16
	global_store_dwordx4 v151, v[52:55], s[22:23] offset:512
	global_store_dwordx4 v151, v[48:51], s[22:23] offset:528
.Lepi3_skipst_4:
	v_add_f32_e32 v168, v172, v173
	v_pk_mul_f32 v[172:173], v[44:45], v[44:45]
	v_pk_fma_f32 v[172:173], v[46:47], v[46:47], v[172:173]
	v_pk_fma_f32 v[172:173], v[40:41], v[40:41], v[172:173]
	v_pk_fma_f32 v[172:173], v[42:43], v[42:43], v[172:173]
	v_pk_fma_f32 v[172:173], v[36:37], v[36:37], v[172:173]
	v_pk_fma_f32 v[172:173], v[38:39], v[38:39], v[172:173]
	v_pk_fma_f32 v[172:173], v[32:33], v[32:33], v[172:173]
	v_pk_fma_f32 v[172:173], v[34:35], v[34:35], v[172:173]
	s_bitcmp1_b32 s19, 5
	s_cbranch_scc0 .Lepi3_skipst_5
	s_add_u32 s22, s98, s42
	s_addc_u32 s23, s99, 0
	global_store_dwordx4 v151, v[44:47], s[22:23]
	global_store_dwordx4 v151, v[40:43], s[22:23] offset:16
	global_store_dwordx4 v151, v[36:39], s[22:23] offset:512
	global_store_dwordx4 v151, v[32:35], s[22:23] offset:528
.Lepi3_skipst_5:
	v_add_f32_e32 v169, v172, v173
	v_pk_mul_f32 v[172:173], v[28:29], v[28:29]
	v_pk_fma_f32 v[172:173], v[30:31], v[30:31], v[172:173]
	v_pk_fma_f32 v[172:173], v[24:25], v[24:25], v[172:173]
	v_pk_fma_f32 v[172:173], v[26:27], v[26:27], v[172:173]
	v_pk_fma_f32 v[172:173], v[20:21], v[20:21], v[172:173]
	v_pk_fma_f32 v[172:173], v[22:23], v[22:23], v[172:173]
	v_pk_fma_f32 v[172:173], v[16:17], v[16:17], v[172:173]
	v_pk_fma_f32 v[172:173], v[18:19], v[18:19], v[172:173]
	s_bitcmp1_b32 s19, 6
	s_cbranch_scc0 .Lepi3_skipst_6
	s_add_u32 s22, s98, s43
	s_addc_u32 s23, s99, 0
	global_store_dwordx4 v151, v[28:31], s[22:23]
	global_store_dwordx4 v151, v[24:27], s[22:23] offset:16
	global_store_dwordx4 v151, v[20:23], s[22:23] offset:512
	global_store_dwordx4 v151, v[16:19], s[22:23] offset:528
.Lepi3_skipst_6:
	v_add_f32_e32 v170, v172, v173
	v_pk_mul_f32 v[172:173], v[12:13], v[12:13]
	v_pk_fma_f32 v[172:173], v[14:15], v[14:15], v[172:173]
	v_pk_fma_f32 v[172:173], v[8:9], v[8:9], v[172:173]
	v_pk_fma_f32 v[172:173], v[10:11], v[10:11], v[172:173]
	v_pk_fma_f32 v[172:173], v[4:5], v[4:5], v[172:173]
	v_pk_fma_f32 v[172:173], v[6:7], v[6:7], v[172:173]
	v_pk_fma_f32 v[172:173], v[0:1], v[0:1], v[172:173]
	v_pk_fma_f32 v[172:173], v[2:3], v[2:3], v[172:173]
	s_bitcmp1_b32 s19, 7
	s_cbranch_scc0 .Lepi3_skipst_7
	s_add_u32 s22, s98, s95
	s_addc_u32 s23, s99, 0
	global_store_dwordx4 v151, v[12:15], s[22:23]
	global_store_dwordx4 v151, v[8:11], s[22:23] offset:16
	global_store_dwordx4 v151, v[4:7], s[22:23] offset:512
	global_store_dwordx4 v151, v[0:3], s[22:23] offset:528
.Lepi3_skipst_7:
	v_add_f32_e32 v171, v172, v173
	ds_bpermute_b32 v155, v153, v168
	ds_bpermute_b32 v156, v153, v169
	ds_bpermute_b32 v157, v153, v170
	ds_bpermute_b32 v132, v153, v171
	s_waitcnt lgkmcnt(0)
	v_add_f32_e32 v168, v168, v155
	v_add_f32_e32 v169, v169, v156
	v_add_f32_e32 v170, v170, v157
	v_add_f32_e32 v171, v171, v132
	ds_bpermute_b32 v155, v154, v168
	ds_bpermute_b32 v156, v154, v169
	ds_bpermute_b32 v157, v154, v170
	ds_bpermute_b32 v132, v154, v171
	s_waitcnt lgkmcnt(0)
	v_add_f32_e32 v168, v168, v155
	v_add_f32_e32 v169, v169, v156
	v_add_f32_e32 v170, v170, v157
	v_add_f32_e32 v171, v171, v132
	s_mov_b64 exec, s[36:37]
	s_bitcmp1_b32 s19, 4
	s_cbranch_scc0 .Lepi3_skipat_4
	global_atomic_add_f32 v152, v168, s[60:61] offset:512
.Lepi3_skipat_4:
	s_bitcmp1_b32 s19, 5
	s_cbranch_scc0 .Lepi3_skipat_5
	global_atomic_add_f32 v152, v169, s[60:61] offset:576
.Lepi3_skipat_5:
	s_bitcmp1_b32 s19, 6
	s_cbranch_scc0 .Lepi3_skipat_6
	global_atomic_add_f32 v152, v170, s[60:61] offset:640
.Lepi3_skipat_6:
	s_bitcmp1_b32 s19, 7
	s_cbranch_scc0 .Lepi3_skipat_7
	global_atomic_add_f32 v152, v171, s[60:61] offset:704
.Lepi3_skipat_7:
	s_mov_b64 exec, -1
	s_andn2_b64 vcc, exec, s[38:39]
	s_mov_b64 s[38:39], -1
	s_cbranch_vccnz .LBB0_609
	s_andn2_b64 vcc, exec, s[72:73]
	s_cbranch_vccnz .LBB0_608
	s_barrier
	s_branch .LBB0_608

; __global__ void __launch_bounds__(512, 2) hymba_mega(Params p) {
;     extern __shared__ __attribute__((aligned(16))) char smem[];
	.amdhsa_kernel _Z10hymba_mega6Params
		.amdhsa_group_segment_fixed_size 256
		.amdhsa_private_segment_fixed_size 0
		.amdhsa_kernarg_size 456
		.amdhsa_user_sgpr_count 2
		.amdhsa_user_sgpr_dispatch_ptr 0
		.amdhsa_user_sgpr_queue_ptr 0
		.amdhsa_user_sgpr_kernarg_segment_ptr 1
		.amdhsa_user_sgpr_dispatch_id 0
		.amdhsa_user_sgpr_kernarg_preload_length 0
		.amdhsa_user_sgpr_kernarg_preload_offset 0
		.amdhsa_user_sgpr_private_segment_size 0
		.amdhsa_uses_dynamic_stack 0
		.amdhsa_enable_private_segment 0
		.amdhsa_system_sgpr_workgroup_id_x 1
		.amdhsa_system_sgpr_workgroup_id_y 0
		.amdhsa_system_sgpr_workgroup_id_z 0
		.amdhsa_system_sgpr_workgroup_info 0
		.amdhsa_system_vgpr_workitem_id 2
		.amdhsa_next_free_vgpr 256
		.amdhsa_next_free_sgpr 102
		.amdhsa_accum_offset 256
		.amdhsa_reserve_vcc 1
		.amdhsa_float_round_mode_32 0
		.amdhsa_float_round_mode_16_64 0
		.amdhsa_float_denorm_mode_32 3
		.amdhsa_float_denorm_mode_16_64 3
		.amdhsa_dx10_clamp 1
		.amdhsa_ieee_mode 1
		.amdhsa_fp16_overflow 0
		.amdhsa_tg_split 0
		.amdhsa_exception_fp_ieee_invalid_op 0
		.amdhsa_exception_fp_denorm_src 0
		.amdhsa_exception_fp_ieee_div_zero 0
		.amdhsa_exception_fp_ieee_overflow 0
		.amdhsa_exception_fp_ieee_underflow 0
		.amdhsa_exception_fp_ieee_inexact 0
		.amdhsa_exception_int_div_zero 0
	.end_amdhsa_kernel

; __global__ void __launch_bounds__(512, 2) hymba_mega(Params p) {
;     extern __shared__ __attribute__((aligned(16))) char smem[];
amdhsa.kernels:
  - .agpr_count:     0
    .args:
      - .offset:         0
        .size:           200
        .value_kind:     by_value
      - .offset:         200
        .size:           4
        .value_kind:     hidden_block_count_x
      - .offset:         204
        .size:           4
        .value_kind:     hidden_block_count_y
      - .offset:         208
        .size:           4
        .value_kind:     hidden_block_count_z
      - .offset:         212
        .size:           2
        .value_kind:     hidden_group_size_x
      - .offset:         214
        .size:           2
        .value_kind:     hidden_group_size_y
      - .offset:         216
        .size:           2
        .value_kind:     hidden_group_size_z
      - .offset:         218
        .size:           2
        .value_kind:     hidden_remainder_x
      - .offset:         220
        .size:           2
        .value_kind:     hidden_remainder_y
      - .offset:         222
        .size:           2
        .value_kind:     hidden_remainder_z
      - .offset:         240
        .size:           8
        .value_kind:     hidden_global_offset_x
      - .offset:         248
        .size:           8
        .value_kind:     hidden_global_offset_y
      - .offset:         256
        .size:           8
        .value_kind:     hidden_global_offset_z
      - .offset:         264
        .size:           2
        .value_kind:     hidden_grid_dims
      - .offset:         320
        .size:           4
        .value_kind:     hidden_dynamic_lds_size
    .group_segment_fixed_size: 256
    .kernarg_segment_align: 8
    .kernarg_segment_size: 456
    .language:       OpenCL C
    .language_version:
      - 2
      - 0
    .max_flat_workgroup_size: 512
    .name:           _Z10hymba_mega6Params
    .private_segment_fixed_size: 0
    .sgpr_count:     108
    .sgpr_spill_count: 27
    .symbol:         _Z10hymba_mega6Params.kd
    .uniform_work_group_size: 1
    .uses_dynamic_stack: false
    .vgpr_count:     256
    .vgpr_spill_count: 0
    .wavefront_size: 64
